# m_comb normaliser-state scan (single workgroup): 4 batches of 64 loads in flight instead of 32 dependent load-wait-store rounds
# speedup vs baseline: 1.0070x; 1.0010x over previous
; DI void phase_m_comb(int wv, const ArgP a, LAS unsigned char* lds, int dry) {
;     ...
;         } else { const int h = tid >> 7; float* p = NST + tid; float C = 0.f;
;             for (int c = 0; c < 256; c += 8) { float d[8];
; #pragma unroll
;                 for (int k = 0; k < 8; ++k) d[k] = p[(size_t)(c + k) * 512];
; #pragma unroll
;                 for (int k = 0; k < 8; ++k) { if (!dry) p[(size_t)(c + k) * 512] = C; C = ga[(c + k) * 4 + h] * C + gb[(c + k) * 4 + h] * d[k]; } } }
.LBB0_1547:
	s_and_b64 vcc, exec, s[0:1]
	s_cbranch_vccz .LBB0_1542
	s_sub_u32 s14, s10, 0x2108000
	s_subb_u32 s15, s11, 0
	s_mov_b64 s[16:17], s[14:15]
	v_lshlrev_b32_e32 v116, 1, v0
	v_mov_b32_e32 v8, 0
	v_mov_b32_e32 v118, v10
	v_add_u32_e32 v119, 0x1000, v10
	s_mov_b32 s0, 0
.Lmn_batch:
	global_load_dword v140, v116, s[14:15]
	s_add_u32 s14, s14, 0x800
	s_addc_u32 s15, s15, 0
	global_load_dword v141, v116, s[14:15]
	s_add_u32 s14, s14, 0x800
	s_addc_u32 s15, s15, 0
	global_load_dword v142, v116, s[14:15]
	s_add_u32 s14, s14, 0x800
	s_addc_u32 s15, s15, 0
	global_load_dword v143, v116, s[14:15]
	s_add_u32 s14, s14, 0x800
	s_addc_u32 s15, s15, 0
	global_load_dword v144, v116, s[14:15]
	s_add_u32 s14, s14, 0x800
	s_addc_u32 s15, s15, 0
	global_load_dword v145, v116, s[14:15]
	s_add_u32 s14, s14, 0x800
	s_addc_u32 s15, s15, 0
	global_load_dword v146, v116, s[14:15]
	s_add_u32 s14, s14, 0x800
	s_addc_u32 s15, s15, 0
	global_load_dword v147, v116, s[14:15]
	s_add_u32 s14, s14, 0x800
	s_addc_u32 s15, s15, 0
	ds_read2_b32 v[12:13], v118 offset0:0 offset1:4
	ds_read2_b32 v[76:77], v119 offset0:0 offset1:4
	ds_read2_b32 v[14:15], v118 offset0:8 offset1:12
	ds_read2_b32 v[78:79], v119 offset0:8 offset1:12
	ds_read2_b32 v[16:17], v118 offset0:16 offset1:20
	ds_read2_b32 v[80:81], v119 offset0:16 offset1:20
	ds_read2_b32 v[18:19], v118 offset0:24 offset1:28
	ds_read2_b32 v[82:83], v119 offset0:24 offset1:28
	global_load_dword v148, v116, s[14:15]
	s_add_u32 s14, s14, 0x800
	s_addc_u32 s15, s15, 0
	global_load_dword v149, v116, s[14:15]
	s_add_u32 s14, s14, 0x800
	s_addc_u32 s15, s15, 0
	global_load_dword v150, v116, s[14:15]
	s_add_u32 s14, s14, 0x800
	s_addc_u32 s15, s15, 0
	global_load_dword v151, v116, s[14:15]
	s_add_u32 s14, s14, 0x800
	s_addc_u32 s15, s15, 0
	global_load_dword v152, v116, s[14:15]
	s_add_u32 s14, s14, 0x800
	s_addc_u32 s15, s15, 0
	global_load_dword v153, v116, s[14:15]
	s_add_u32 s14, s14, 0x800
	s_addc_u32 s15, s15, 0
	global_load_dword v154, v116, s[14:15]
	s_add_u32 s14, s14, 0x800
	s_addc_u32 s15, s15, 0
	global_load_dword v155, v116, s[14:15]
	s_add_u32 s14, s14, 0x800
	s_addc_u32 s15, s15, 0
	s_waitcnt lgkmcnt(0)
	ds_read2_b32 v[20:21], v118 offset0:32 offset1:36
	ds_read2_b32 v[84:85], v119 offset0:32 offset1:36
	ds_read2_b32 v[22:23], v118 offset0:40 offset1:44
	ds_read2_b32 v[86:87], v119 offset0:40 offset1:44
	ds_read2_b32 v[24:25], v118 offset0:48 offset1:52
	ds_read2_b32 v[88:89], v119 offset0:48 offset1:52
	ds_read2_b32 v[26:27], v118 offset0:56 offset1:60
	ds_read2_b32 v[90:91], v119 offset0:56 offset1:60
	global_load_dword v156, v116, s[14:15]
	s_add_u32 s14, s14, 0x800
	s_addc_u32 s15, s15, 0
	global_load_dword v157, v116, s[14:15]
	s_add_u32 s14, s14, 0x800
	s_addc_u32 s15, s15, 0
	global_load_dword v158, v116, s[14:15]
	s_add_u32 s14, s14, 0x800
	s_addc_u32 s15, s15, 0
	global_load_dword v159, v116, s[14:15]
	s_add_u32 s14, s14, 0x800
	s_addc_u32 s15, s15, 0
	global_load_dword v160, v116, s[14:15]
	s_add_u32 s14, s14, 0x800
	s_addc_u32 s15, s15, 0
	global_load_dword v161, v116, s[14:15]
	s_add_u32 s14, s14, 0x800
	s_addc_u32 s15, s15, 0
	global_load_dword v162, v116, s[14:15]
	s_add_u32 s14, s14, 0x800
	s_addc_u32 s15, s15, 0
	global_load_dword v163, v116, s[14:15]
	s_add_u32 s14, s14, 0x800
	s_addc_u32 s15, s15, 0
	s_waitcnt lgkmcnt(0)
	ds_read2_b32 v[28:29], v118 offset0:64 offset1:68
	ds_read2_b32 v[92:93], v119 offset0:64 offset1:68
	ds_read2_b32 v[30:31], v118 offset0:72 offset1:76
	ds_read2_b32 v[94:95], v119 offset0:72 offset1:76
	ds_read2_b32 v[32:33], v118 offset0:80 offset1:84
	ds_read2_b32 v[96:97], v119 offset0:80 offset1:84
	ds_read2_b32 v[34:35], v118 offset0:88 offset1:92
	ds_read2_b32 v[98:99], v119 offset0:88 offset1:92
	global_load_dword v164, v116, s[14:15]
	s_add_u32 s14, s14, 0x800
	s_addc_u32 s15, s15, 0
	global_load_dword v165, v116, s[14:15]
	s_add_u32 s14, s14, 0x800
	s_addc_u32 s15, s15, 0
	global_load_dword v166, v116, s[14:15]
	s_add_u32 s14, s14, 0x800
	s_addc_u32 s15, s15, 0
	global_load_dword v167, v116, s[14:15]
	s_add_u32 s14, s14, 0x800
	s_addc_u32 s15, s15, 0
	global_load_dword v168, v116, s[14:15]
	s_add_u32 s14, s14, 0x800
	s_addc_u32 s15, s15, 0
	global_load_dword v169, v116, s[14:15]
	s_add_u32 s14, s14, 0x800
	s_addc_u32 s15, s15, 0
	global_load_dword v170, v116, s[14:15]
	s_add_u32 s14, s14, 0x800
	s_addc_u32 s15, s15, 0
	global_load_dword v171, v116, s[14:15]
	s_add_u32 s14, s14, 0x800
	s_addc_u32 s15, s15, 0
	s_waitcnt lgkmcnt(0)
	ds_read2_b32 v[36:37], v118 offset0:96 offset1:100
	ds_read2_b32 v[100:101], v119 offset0:96 offset1:100
	ds_read2_b32 v[38:39], v118 offset0:104 offset1:108
	ds_read2_b32 v[102:103], v119 offset0:104 offset1:108
	ds_read2_b32 v[40:41], v118 offset0:112 offset1:116
	ds_read2_b32 v[104:105], v119 offset0:112 offset1:116
	ds_read2_b32 v[42:43], v118 offset0:120 offset1:124
	ds_read2_b32 v[106:107], v119 offset0:120 offset1:124
	global_load_dword v172, v116, s[14:15]
	s_add_u32 s14, s14, 0x800
	s_addc_u32 s15, s15, 0
	global_load_dword v173, v116, s[14:15]
	s_add_u32 s14, s14, 0x800
	s_addc_u32 s15, s15, 0
	global_load_dword v174, v116, s[14:15]
	s_add_u32 s14, s14, 0x800
	s_addc_u32 s15, s15, 0
	global_load_dword v175, v116, s[14:15]
	s_add_u32 s14, s14, 0x800
	s_addc_u32 s15, s15, 0
	global_load_dword v176, v116, s[14:15]
	s_add_u32 s14, s14, 0x800
	s_addc_u32 s15, s15, 0
	global_load_dword v177, v116, s[14:15]
	s_add_u32 s14, s14, 0x800
	s_addc_u32 s15, s15, 0
	global_load_dword v178, v116, s[14:15]
	s_add_u32 s14, s14, 0x800
	s_addc_u32 s15, s15, 0
	global_load_dword v179, v116, s[14:15]
	s_add_u32 s14, s14, 0x800
	s_addc_u32 s15, s15, 0
	s_waitcnt lgkmcnt(0)
; DI void phase_m_comb(int wv, const ArgP a, LAS unsigned char* lds, int dry) {
;     ...
;             for (int c = 0; c < 256; c += 8) { float d[8];
; #pragma unroll
;                 for (int k = 0; k < 8; ++k) d[k] = p[(size_t)(c + k) * 512];
; #pragma unroll
;                 for (int k = 0; k < 8; ++k) { if (!dry) p[(size_t)(c + k) * 512] = C; C = ga[(c + k) * 4 + h] * C + gb[(c + k) * 4 + h] * d[k]; } } }
	ds_read2_b32 v[44:45], v118 offset0:128 offset1:132
	ds_read2_b32 v[108:109], v119 offset0:128 offset1:132
	ds_read2_b32 v[46:47], v118 offset0:136 offset1:140
	ds_read2_b32 v[110:111], v119 offset0:136 offset1:140
	ds_read2_b32 v[48:49], v118 offset0:144 offset1:148
	ds_read2_b32 v[112:113], v119 offset0:144 offset1:148
	ds_read2_b32 v[50:51], v118 offset0:152 offset1:156
	ds_read2_b32 v[114:115], v119 offset0:152 offset1:156
	global_load_dword v180, v116, s[14:15]
	s_add_u32 s14, s14, 0x800
	s_addc_u32 s15, s15, 0
	global_load_dword v181, v116, s[14:15]
	s_add_u32 s14, s14, 0x800
	s_addc_u32 s15, s15, 0
	global_load_dword v182, v116, s[14:15]
	s_add_u32 s14, s14, 0x800
	s_addc_u32 s15, s15, 0
	global_load_dword v183, v116, s[14:15]
	s_add_u32 s14, s14, 0x800
	s_addc_u32 s15, s15, 0
	global_load_dword v184, v116, s[14:15]
	s_add_u32 s14, s14, 0x800
	s_addc_u32 s15, s15, 0
	global_load_dword v185, v116, s[14:15]
	s_add_u32 s14, s14, 0x800
	s_addc_u32 s15, s15, 0
	global_load_dword v186, v116, s[14:15]
	s_add_u32 s14, s14, 0x800
	s_addc_u32 s15, s15, 0
	global_load_dword v187, v116, s[14:15]
	s_add_u32 s14, s14, 0x800
	s_addc_u32 s15, s15, 0
	s_waitcnt lgkmcnt(0)
	ds_read2_b32 v[52:53], v118 offset0:160 offset1:164
	ds_read2_b32 v[208:209], v119 offset0:160 offset1:164
	ds_read2_b32 v[54:55], v118 offset0:168 offset1:172
	ds_read2_b32 v[210:211], v119 offset0:168 offset1:172
	ds_read2_b32 v[56:57], v118 offset0:176 offset1:180
	ds_read2_b32 v[212:213], v119 offset0:176 offset1:180
	ds_read2_b32 v[58:59], v118 offset0:184 offset1:188
	ds_read2_b32 v[214:215], v119 offset0:184 offset1:188
	global_load_dword v188, v116, s[14:15]
	s_add_u32 s14, s14, 0x800
	s_addc_u32 s15, s15, 0
	global_load_dword v189, v116, s[14:15]
	s_add_u32 s14, s14, 0x800
	s_addc_u32 s15, s15, 0
	global_load_dword v190, v116, s[14:15]
	s_add_u32 s14, s14, 0x800
	s_addc_u32 s15, s15, 0
	global_load_dword v191, v116, s[14:15]
	s_add_u32 s14, s14, 0x800
	s_addc_u32 s15, s15, 0
	global_load_dword v196, v116, s[14:15]
	s_add_u32 s14, s14, 0x800
	s_addc_u32 s15, s15, 0
	global_load_dword v197, v116, s[14:15]
	s_add_u32 s14, s14, 0x800
	s_addc_u32 s15, s15, 0
	global_load_dword v198, v116, s[14:15]
	s_add_u32 s14, s14, 0x800
	s_addc_u32 s15, s15, 0
	global_load_dword v199, v116, s[14:15]
	s_add_u32 s14, s14, 0x800
	s_addc_u32 s15, s15, 0
	s_waitcnt lgkmcnt(0)
	ds_read2_b32 v[60:61], v118 offset0:192 offset1:196
	ds_read2_b32 v[216:217], v119 offset0:192 offset1:196
	ds_read2_b32 v[62:63], v118 offset0:200 offset1:204
	ds_read2_b32 v[218:219], v119 offset0:200 offset1:204
	ds_read2_b32 v[64:65], v118 offset0:208 offset1:212
	ds_read2_b32 v[220:221], v119 offset0:208 offset1:212
	ds_read2_b32 v[66:67], v118 offset0:216 offset1:220
	ds_read2_b32 v[222:223], v119 offset0:216 offset1:220
	global_load_dword v200, v116, s[14:15]
	s_add_u32 s14, s14, 0x800
	s_addc_u32 s15, s15, 0
	global_load_dword v201, v116, s[14:15]
	s_add_u32 s14, s14, 0x800
	s_addc_u32 s15, s15, 0
	global_load_dword v202, v116, s[14:15]
	s_add_u32 s14, s14, 0x800
	s_addc_u32 s15, s15, 0
	global_load_dword v203, v116, s[14:15]
	s_add_u32 s14, s14, 0x800
	s_addc_u32 s15, s15, 0
	global_load_dword v204, v116, s[14:15]
	s_add_u32 s14, s14, 0x800
	s_addc_u32 s15, s15, 0
	global_load_dword v205, v116, s[14:15]
	s_add_u32 s14, s14, 0x800
	s_addc_u32 s15, s15, 0
	global_load_dword v206, v116, s[14:15]
	s_add_u32 s14, s14, 0x800
	s_addc_u32 s15, s15, 0
	global_load_dword v207, v116, s[14:15]
	s_add_u32 s14, s14, 0x800
	s_addc_u32 s15, s15, 0
	s_waitcnt lgkmcnt(0)
	ds_read2_b32 v[68:69], v118 offset0:224 offset1:228
	ds_read2_b32 v[224:225], v119 offset0:224 offset1:228
	ds_read2_b32 v[70:71], v118 offset0:232 offset1:236
	ds_read2_b32 v[226:227], v119 offset0:232 offset1:236
	ds_read2_b32 v[72:73], v118 offset0:240 offset1:244
	ds_read2_b32 v[228:229], v119 offset0:240 offset1:244
	ds_read2_b32 v[74:75], v118 offset0:248 offset1:252
	ds_read2_b32 v[230:231], v119 offset0:248 offset1:252
	s_waitcnt lgkmcnt(0)
	s_waitcnt vmcnt(63)
	global_store_dword v116, v8, s[16:17]
	v_mul_f32_e32 v120, v140, v76
	s_add_u32 s16, s16, 0x800
	s_addc_u32 s17, s17, 0
	v_fma_f32 v8, v8, v12, v120
	s_waitcnt vmcnt(63)
	global_store_dword v116, v8, s[16:17]
	v_mul_f32_e32 v120, v141, v77
	s_add_u32 s16, s16, 0x800
	s_addc_u32 s17, s17, 0
	v_fma_f32 v8, v8, v13, v120
	s_waitcnt vmcnt(63)
	global_store_dword v116, v8, s[16:17]
	v_mul_f32_e32 v120, v142, v78
	s_add_u32 s16, s16, 0x800
	s_addc_u32 s17, s17, 0
	v_fma_f32 v8, v8, v14, v120
	s_waitcnt vmcnt(63)
	global_store_dword v116, v8, s[16:17]
	v_mul_f32_e32 v120, v143, v79
	s_add_u32 s16, s16, 0x800
	s_addc_u32 s17, s17, 0
	v_fma_f32 v8, v8, v15, v120
	s_waitcnt vmcnt(63)
	global_store_dword v116, v8, s[16:17]
	v_mul_f32_e32 v120, v144, v80
	s_add_u32 s16, s16, 0x800
	s_addc_u32 s17, s17, 0
	v_fma_f32 v8, v8, v16, v120
	s_waitcnt vmcnt(63)
	global_store_dword v116, v8, s[16:17]
	v_mul_f32_e32 v120, v145, v81
	s_add_u32 s16, s16, 0x800
	s_addc_u32 s17, s17, 0
	v_fma_f32 v8, v8, v17, v120
	s_waitcnt vmcnt(63)
	global_store_dword v116, v8, s[16:17]
	v_mul_f32_e32 v120, v146, v82
	s_add_u32 s16, s16, 0x800
	s_addc_u32 s17, s17, 0
	v_fma_f32 v8, v8, v18, v120
	s_waitcnt vmcnt(63)
	global_store_dword v116, v8, s[16:17]
	v_mul_f32_e32 v120, v147, v83
	s_add_u32 s16, s16, 0x800
	s_addc_u32 s17, s17, 0
	v_fma_f32 v8, v8, v19, v120
	s_waitcnt vmcnt(63)
	global_store_dword v116, v8, s[16:17]
	v_mul_f32_e32 v120, v148, v84
	s_add_u32 s16, s16, 0x800
	s_addc_u32 s17, s17, 0
	v_fma_f32 v8, v8, v20, v120
	s_waitcnt vmcnt(63)
; DI void phase_m_comb(int wv, const ArgP a, LAS unsigned char* lds, int dry) {
;     ...
;             for (int c = 0; c < 256; c += 8) { float d[8];
; #pragma unroll
;                 for (int k = 0; k < 8; ++k) d[k] = p[(size_t)(c + k) * 512];
; #pragma unroll
;                 for (int k = 0; k < 8; ++k) { if (!dry) p[(size_t)(c + k) * 512] = C; C = ga[(c + k) * 4 + h] * C + gb[(c + k) * 4 + h] * d[k]; } } }
	global_store_dword v116, v8, s[16:17]
	v_mul_f32_e32 v120, v149, v85
	s_add_u32 s16, s16, 0x800
	s_addc_u32 s17, s17, 0
	v_fma_f32 v8, v8, v21, v120
	s_waitcnt vmcnt(63)
	global_store_dword v116, v8, s[16:17]
	v_mul_f32_e32 v120, v150, v86
	s_add_u32 s16, s16, 0x800
	s_addc_u32 s17, s17, 0
	v_fma_f32 v8, v8, v22, v120
	s_waitcnt vmcnt(63)
	global_store_dword v116, v8, s[16:17]
	v_mul_f32_e32 v120, v151, v87
	s_add_u32 s16, s16, 0x800
	s_addc_u32 s17, s17, 0
	v_fma_f32 v8, v8, v23, v120
	s_waitcnt vmcnt(63)
	global_store_dword v116, v8, s[16:17]
	v_mul_f32_e32 v120, v152, v88
	s_add_u32 s16, s16, 0x800
	s_addc_u32 s17, s17, 0
	v_fma_f32 v8, v8, v24, v120
	s_waitcnt vmcnt(63)
	global_store_dword v116, v8, s[16:17]
	v_mul_f32_e32 v120, v153, v89
	s_add_u32 s16, s16, 0x800
	s_addc_u32 s17, s17, 0
	v_fma_f32 v8, v8, v25, v120
	s_waitcnt vmcnt(63)
	global_store_dword v116, v8, s[16:17]
	v_mul_f32_e32 v120, v154, v90
	s_add_u32 s16, s16, 0x800
	s_addc_u32 s17, s17, 0
	v_fma_f32 v8, v8, v26, v120
	s_waitcnt vmcnt(63)
	global_store_dword v116, v8, s[16:17]
	v_mul_f32_e32 v120, v155, v91
	s_add_u32 s16, s16, 0x800
	s_addc_u32 s17, s17, 0
	v_fma_f32 v8, v8, v27, v120
	s_waitcnt vmcnt(63)
	global_store_dword v116, v8, s[16:17]
	v_mul_f32_e32 v120, v156, v92
	s_add_u32 s16, s16, 0x800
	s_addc_u32 s17, s17, 0
	v_fma_f32 v8, v8, v28, v120
	s_waitcnt vmcnt(63)
	global_store_dword v116, v8, s[16:17]
	v_mul_f32_e32 v120, v157, v93
	s_add_u32 s16, s16, 0x800
	s_addc_u32 s17, s17, 0
	v_fma_f32 v8, v8, v29, v120
	s_waitcnt vmcnt(63)
	global_store_dword v116, v8, s[16:17]
	v_mul_f32_e32 v120, v158, v94
	s_add_u32 s16, s16, 0x800
	s_addc_u32 s17, s17, 0
	v_fma_f32 v8, v8, v30, v120
	s_waitcnt vmcnt(63)
	global_store_dword v116, v8, s[16:17]
	v_mul_f32_e32 v120, v159, v95
	s_add_u32 s16, s16, 0x800
	s_addc_u32 s17, s17, 0
	v_fma_f32 v8, v8, v31, v120
	s_waitcnt vmcnt(63)
	global_store_dword v116, v8, s[16:17]
	v_mul_f32_e32 v120, v160, v96
	s_add_u32 s16, s16, 0x800
	s_addc_u32 s17, s17, 0
	v_fma_f32 v8, v8, v32, v120
	s_waitcnt vmcnt(63)
	global_store_dword v116, v8, s[16:17]
	v_mul_f32_e32 v120, v161, v97
	s_add_u32 s16, s16, 0x800
	s_addc_u32 s17, s17, 0
	v_fma_f32 v8, v8, v33, v120
	s_waitcnt vmcnt(63)
	global_store_dword v116, v8, s[16:17]
	v_mul_f32_e32 v120, v162, v98
	s_add_u32 s16, s16, 0x800
	s_addc_u32 s17, s17, 0
	v_fma_f32 v8, v8, v34, v120
	s_waitcnt vmcnt(63)
	global_store_dword v116, v8, s[16:17]
	v_mul_f32_e32 v120, v163, v99
	s_add_u32 s16, s16, 0x800
	s_addc_u32 s17, s17, 0
	v_fma_f32 v8, v8, v35, v120
	s_waitcnt vmcnt(63)
	global_store_dword v116, v8, s[16:17]
	v_mul_f32_e32 v120, v164, v100
	s_add_u32 s16, s16, 0x800
	s_addc_u32 s17, s17, 0
	v_fma_f32 v8, v8, v36, v120
	s_waitcnt vmcnt(63)
	global_store_dword v116, v8, s[16:17]
	v_mul_f32_e32 v120, v165, v101
	s_add_u32 s16, s16, 0x800
	s_addc_u32 s17, s17, 0
	v_fma_f32 v8, v8, v37, v120
	s_waitcnt vmcnt(63)
	global_store_dword v116, v8, s[16:17]
	v_mul_f32_e32 v120, v166, v102
	s_add_u32 s16, s16, 0x800
	s_addc_u32 s17, s17, 0
	v_fma_f32 v8, v8, v38, v120
	s_waitcnt vmcnt(63)
	global_store_dword v116, v8, s[16:17]
	v_mul_f32_e32 v120, v167, v103
	s_add_u32 s16, s16, 0x800
	s_addc_u32 s17, s17, 0
	v_fma_f32 v8, v8, v39, v120
	s_waitcnt vmcnt(63)
	global_store_dword v116, v8, s[16:17]
	v_mul_f32_e32 v120, v168, v104
	s_add_u32 s16, s16, 0x800
	s_addc_u32 s17, s17, 0
	v_fma_f32 v8, v8, v40, v120
	s_waitcnt vmcnt(63)
	global_store_dword v116, v8, s[16:17]
	v_mul_f32_e32 v120, v169, v105
	s_add_u32 s16, s16, 0x800
	s_addc_u32 s17, s17, 0
	v_fma_f32 v8, v8, v41, v120
	s_waitcnt vmcnt(63)
	global_store_dword v116, v8, s[16:17]
	v_mul_f32_e32 v120, v170, v106
	s_add_u32 s16, s16, 0x800
	s_addc_u32 s17, s17, 0
	v_fma_f32 v8, v8, v42, v120
	s_waitcnt vmcnt(63)
	global_store_dword v116, v8, s[16:17]
	v_mul_f32_e32 v120, v171, v107
	s_add_u32 s16, s16, 0x800
	s_addc_u32 s17, s17, 0
	v_fma_f32 v8, v8, v43, v120
	s_waitcnt vmcnt(63)
	global_store_dword v116, v8, s[16:17]
	v_mul_f32_e32 v120, v172, v108
	s_add_u32 s16, s16, 0x800
	s_addc_u32 s17, s17, 0
	v_fma_f32 v8, v8, v44, v120
	s_waitcnt vmcnt(63)
	global_store_dword v116, v8, s[16:17]
	v_mul_f32_e32 v120, v173, v109
	s_add_u32 s16, s16, 0x800
	s_addc_u32 s17, s17, 0
	v_fma_f32 v8, v8, v45, v120
	s_waitcnt vmcnt(63)
	global_store_dword v116, v8, s[16:17]
	v_mul_f32_e32 v120, v174, v110
	s_add_u32 s16, s16, 0x800
	s_addc_u32 s17, s17, 0
	v_fma_f32 v8, v8, v46, v120
	s_waitcnt vmcnt(63)
	global_store_dword v116, v8, s[16:17]
	v_mul_f32_e32 v120, v175, v111
	s_add_u32 s16, s16, 0x800
	s_addc_u32 s17, s17, 0
	v_fma_f32 v8, v8, v47, v120
	s_waitcnt vmcnt(63)
	global_store_dword v116, v8, s[16:17]
	v_mul_f32_e32 v120, v176, v112
	s_add_u32 s16, s16, 0x800
	s_addc_u32 s17, s17, 0
	v_fma_f32 v8, v8, v48, v120
	s_waitcnt vmcnt(63)
; DI void phase_m_comb(int wv, const ArgP a, LAS unsigned char* lds, int dry) {
;     ...
;             for (int c = 0; c < 256; c += 8) { float d[8];
; #pragma unroll
;                 for (int k = 0; k < 8; ++k) d[k] = p[(size_t)(c + k) * 512];
; #pragma unroll
;                 for (int k = 0; k < 8; ++k) { if (!dry) p[(size_t)(c + k) * 512] = C; C = ga[(c + k) * 4 + h] * C + gb[(c + k) * 4 + h] * d[k]; } } }
	global_store_dword v116, v8, s[16:17]
	v_mul_f32_e32 v120, v177, v113
	s_add_u32 s16, s16, 0x800
	s_addc_u32 s17, s17, 0
	v_fma_f32 v8, v8, v49, v120
	s_waitcnt vmcnt(63)
	global_store_dword v116, v8, s[16:17]
	v_mul_f32_e32 v120, v178, v114
	s_add_u32 s16, s16, 0x800
	s_addc_u32 s17, s17, 0
	v_fma_f32 v8, v8, v50, v120
	s_waitcnt vmcnt(63)
	global_store_dword v116, v8, s[16:17]
	v_mul_f32_e32 v120, v179, v115
	s_add_u32 s16, s16, 0x800
	s_addc_u32 s17, s17, 0
	v_fma_f32 v8, v8, v51, v120
	s_waitcnt vmcnt(63)
	global_store_dword v116, v8, s[16:17]
	v_mul_f32_e32 v120, v180, v208
	s_add_u32 s16, s16, 0x800
	s_addc_u32 s17, s17, 0
	v_fma_f32 v8, v8, v52, v120
	s_waitcnt vmcnt(63)
	global_store_dword v116, v8, s[16:17]
	v_mul_f32_e32 v120, v181, v209
	s_add_u32 s16, s16, 0x800
	s_addc_u32 s17, s17, 0
	v_fma_f32 v8, v8, v53, v120
	s_waitcnt vmcnt(63)
	global_store_dword v116, v8, s[16:17]
	v_mul_f32_e32 v120, v182, v210
	s_add_u32 s16, s16, 0x800
	s_addc_u32 s17, s17, 0
	v_fma_f32 v8, v8, v54, v120
	s_waitcnt vmcnt(63)
	global_store_dword v116, v8, s[16:17]
	v_mul_f32_e32 v120, v183, v211
	s_add_u32 s16, s16, 0x800
	s_addc_u32 s17, s17, 0
	v_fma_f32 v8, v8, v55, v120
	s_waitcnt vmcnt(63)
	global_store_dword v116, v8, s[16:17]
	v_mul_f32_e32 v120, v184, v212
	s_add_u32 s16, s16, 0x800
	s_addc_u32 s17, s17, 0
	v_fma_f32 v8, v8, v56, v120
	s_waitcnt vmcnt(63)
	global_store_dword v116, v8, s[16:17]
	v_mul_f32_e32 v120, v185, v213
	s_add_u32 s16, s16, 0x800
	s_addc_u32 s17, s17, 0
	v_fma_f32 v8, v8, v57, v120
	s_waitcnt vmcnt(63)
	global_store_dword v116, v8, s[16:17]
	v_mul_f32_e32 v120, v186, v214
	s_add_u32 s16, s16, 0x800
	s_addc_u32 s17, s17, 0
	v_fma_f32 v8, v8, v58, v120
	s_waitcnt vmcnt(63)
	global_store_dword v116, v8, s[16:17]
	v_mul_f32_e32 v120, v187, v215
	s_add_u32 s16, s16, 0x800
	s_addc_u32 s17, s17, 0
	v_fma_f32 v8, v8, v59, v120
	s_waitcnt vmcnt(63)
	global_store_dword v116, v8, s[16:17]
	v_mul_f32_e32 v120, v188, v216
	s_add_u32 s16, s16, 0x800
	s_addc_u32 s17, s17, 0
	v_fma_f32 v8, v8, v60, v120
	s_waitcnt vmcnt(63)
	global_store_dword v116, v8, s[16:17]
	v_mul_f32_e32 v120, v189, v217
	s_add_u32 s16, s16, 0x800
	s_addc_u32 s17, s17, 0
	v_fma_f32 v8, v8, v61, v120
	s_waitcnt vmcnt(63)
	global_store_dword v116, v8, s[16:17]
	v_mul_f32_e32 v120, v190, v218
	s_add_u32 s16, s16, 0x800
	s_addc_u32 s17, s17, 0
	v_fma_f32 v8, v8, v62, v120
	s_waitcnt vmcnt(63)
	global_store_dword v116, v8, s[16:17]
	v_mul_f32_e32 v120, v191, v219
	s_add_u32 s16, s16, 0x800
	s_addc_u32 s17, s17, 0
	v_fma_f32 v8, v8, v63, v120
	s_waitcnt vmcnt(63)
	global_store_dword v116, v8, s[16:17]
	v_mul_f32_e32 v120, v196, v220
	s_add_u32 s16, s16, 0x800
	s_addc_u32 s17, s17, 0
	v_fma_f32 v8, v8, v64, v120
	s_waitcnt vmcnt(63)
	global_store_dword v116, v8, s[16:17]
	v_mul_f32_e32 v120, v197, v221
	s_add_u32 s16, s16, 0x800
	s_addc_u32 s17, s17, 0
	v_fma_f32 v8, v8, v65, v120
	s_waitcnt vmcnt(63)
	global_store_dword v116, v8, s[16:17]
	v_mul_f32_e32 v120, v198, v222
	s_add_u32 s16, s16, 0x800
	s_addc_u32 s17, s17, 0
	v_fma_f32 v8, v8, v66, v120
	s_waitcnt vmcnt(63)
	global_store_dword v116, v8, s[16:17]
	v_mul_f32_e32 v120, v199, v223
	s_add_u32 s16, s16, 0x800
	s_addc_u32 s17, s17, 0
	v_fma_f32 v8, v8, v67, v120
	s_waitcnt vmcnt(63)
	global_store_dword v116, v8, s[16:17]
	v_mul_f32_e32 v120, v200, v224
	s_add_u32 s16, s16, 0x800
	s_addc_u32 s17, s17, 0
	v_fma_f32 v8, v8, v68, v120
	s_waitcnt vmcnt(63)
	global_store_dword v116, v8, s[16:17]
	v_mul_f32_e32 v120, v201, v225
	s_add_u32 s16, s16, 0x800
	s_addc_u32 s17, s17, 0
	v_fma_f32 v8, v8, v69, v120
	s_waitcnt vmcnt(63)
	global_store_dword v116, v8, s[16:17]
	v_mul_f32_e32 v120, v202, v226
	s_add_u32 s16, s16, 0x800
	s_addc_u32 s17, s17, 0
	v_fma_f32 v8, v8, v70, v120
	s_waitcnt vmcnt(63)
	global_store_dword v116, v8, s[16:17]
	v_mul_f32_e32 v120, v203, v227
	s_add_u32 s16, s16, 0x800
	s_addc_u32 s17, s17, 0
	v_fma_f32 v8, v8, v71, v120
	s_waitcnt vmcnt(63)
	global_store_dword v116, v8, s[16:17]
	v_mul_f32_e32 v120, v204, v228
	s_add_u32 s16, s16, 0x800
	s_addc_u32 s17, s17, 0
	v_fma_f32 v8, v8, v72, v120
	s_waitcnt vmcnt(63)
	global_store_dword v116, v8, s[16:17]
	v_mul_f32_e32 v120, v205, v229
	s_add_u32 s16, s16, 0x800
	s_addc_u32 s17, s17, 0
	v_fma_f32 v8, v8, v73, v120
	s_waitcnt vmcnt(63)
	global_store_dword v116, v8, s[16:17]
	v_mul_f32_e32 v120, v206, v230
	s_add_u32 s16, s16, 0x800
	s_addc_u32 s17, s17, 0
	v_fma_f32 v8, v8, v74, v120
	s_waitcnt vmcnt(63)
	global_store_dword v116, v8, s[16:17]
	v_mul_f32_e32 v120, v207, v231
	s_add_u32 s16, s16, 0x800
	s_addc_u32 s17, s17, 0
	v_fma_f32 v8, v8, v75, v120
	v_add_u32_e32 v118, 0x400, v118
	v_add_u32_e32 v119, 0x400, v119
	s_add_i32 s0, s0, 64
	s_cmpk_lt_u32 s0, 0x100
	s_cbranch_scc1 .Lmn_batch
	s_branch .LBB0_1542
